# P1 GEMM rounds processed in reverse order (gate tiles first, QKV/HG last) so the next phase finds its inputs cache-resident
# speedup vs baseline: 1.0032x; 1.0032x over previous
.LBB0_248:
.LBB0_249:
	s_cmp_lt_i32 s86, 2
	s_cselect_b64 s[2:3], -1, 0
	s_add_u32 s62, s84, 0xb000000
	s_addc_u32 s63, s85, 0
	s_add_u32 s64, s84, 0xf800000
	s_addc_u32 s65, s85, 0
	s_add_u32 s70, s84, 0x13800000
	s_addc_u32 s71, s85, 0
	s_add_u32 s4, s84, 0x17800000
	s_addc_u32 s5, s85, 0
	s_and_b64 s[0:1], s[2:3], s[0:1]
	v_writelane_b32 v228, s4, 14
	s_andn2_b64 vcc, exec, s[0:1]
	s_nop 0
	v_writelane_b32 v228, s5, 15
	s_cbranch_vccnz .LBB0_392
	s_add_u32 s3, s84, 0x200000
	s_addc_u32 s34, s85, 0
	s_abs_i32 s2, s88
	v_cvt_f32_u32_e32 v1, s2
	s_sub_i32 s5, 0, s2
	s_ashr_i32 s4, s88, 31
	v_readfirstlane_b32 s10, v165
	v_rcp_iflag_f32_e32 v1, v1
	s_nop 0
	v_mul_f32_e32 v1, 0x4f7ffffe, v1
	v_cvt_u32_f32_e32 v1, v1
	s_nop 0
	v_readfirstlane_b32 s6, v1
	s_mul_i32 s5, s5, s6
	s_mul_hi_u32 s5, s6, s5
	s_add_i32 s6, s6, s5
	s_mul_hi_u32 s5, s6, 0x600
	s_mul_i32 s6, s5, s2
	s_sub_i32 s6, 0x600, s6
	s_add_i32 s7, s5, 1
	s_sub_i32 s8, s6, s2
	s_cmp_ge_u32 s6, s2
	s_cselect_b32 s5, s7, s5
	s_cselect_b32 s6, s8, s6
	s_add_i32 s7, s5, 1
	s_cmp_ge_u32 s6, s2
	s_cselect_b32 s2, s7, s5
	s_xor_b32 s2, s2, s4
	s_sub_i32 s35, s2, s4
	s_mul_i32 s2, s35, s88
	s_sub_i32 s12, 0x600, s2
	s_cmp_lt_i32 s94, s12
	s_cselect_b64 s[4:5], -1, 0
	s_add_i32 s8, s35, -1
	s_mul_i32 s8, s8, s88
	s_add_i32 s8, s8, s94
	s_cmp_gt_i32 s35, 0
	s_mov_b64 s[6:7], -1
	s_cbranch_scc1 .LBB0_253
	s_cmp_eq_u32 s35, 0
	s_cselect_b64 s[6:7], -1, 0
	s_and_b64 s[6:7], s[6:7], s[4:5]
	s_and_b64 vcc, exec, s[6:7]
	s_cbranch_vccz .LBB0_256
	s_abs_i32 s6, s12
	v_cvt_f32_u32_e32 v1, s6
	s_sub_i32 s9, 0, s6
	s_abs_i32 s8, s94
	s_ashr_i32 s7, s94, 31
	v_rcp_iflag_f32_e32 v1, v1
	s_nop 0
	v_mul_f32_e32 v1, 0x4f7ffffe, v1
	v_cvt_u32_f32_e32 v1, v1
	s_nop 0
	v_readfirstlane_b32 s11, v1
	s_mul_i32 s9, s9, s11
	s_mul_hi_u32 s9, s11, s9
	s_add_i32 s11, s11, s9
	s_mul_hi_u32 s9, s8, s11
	s_mul_i32 s9, s9, s6
	s_sub_i32 s8, s8, s9
	s_sub_i32 s9, s8, s6
	s_cmp_ge_u32 s8, s6
	s_cselect_b32 s8, s9, s8
	s_sub_i32 s9, s8, s6
	s_cmp_ge_u32 s8, s6
	s_cselect_b32 s6, s9, s8
	s_xor_b32 s6, s6, s7
	s_sub_i32 s8, s6, s7
	s_mov_b64 s[6:7], -1

.LBB0_269:
	s_sub_i32 s2, s35, s41
	s_add_i32 s2, s2, -1
	s_mul_i32 s2, s2, s88
	s_add_i32 s2, s2, s94
	s_mov_b64 s[20:21], -1
